# glr_item (L1 gate-rank partials): all 32 fragment loads issued up front into spare VGPR quads instead of a 2-step lookahead; MFMAs consume with counted waits
# speedup vs baseline: 1.0099x; 1.0043x over previous
.LBB0_1005:
	s_lshl_b32 s0, s2, 3
	v_readlane_b32 s1, v251, 51
	s_add_i32 s6, s1, s0
	s_add_u32 s0, s34, 0xf400000
	s_addc_u32 s1, s35, 0
	s_ashr_i32 s6, s6, 2
	s_ashr_i32 s7, s6, 31
	v_and_b32_e32 v119, 31, v0
	s_lshl_b64 s[6:7], s[6:7], 5
	v_or_b32_e32 v2, s6, v119
	v_mov_b32_e32 v3, s7
	s_bfe_u32 s10, s89, 0x20006
	v_lshlrev_b64 v[2:3], 11, v[2:3]
	v_bfe_u32 v24, v0, 5, 1
	s_mov_b32 s9, 0
	v_lshl_add_u64 v[2:3], s[58:59], 0, v[2:3]
	s_lshl_b32 s8, s10, 9
	v_mov_b32_e32 v19, 0
	v_lshl_add_u64 v[2:3], v[2:3], 0, s[8:9]
	v_lshlrev_b32_e32 v18, 4, v24
	v_lshlrev_b32_e32 v74, 11, v0
	v_lshl_add_u64 v[20:21], v[2:3], 0, v[18:19]
	v_and_b32_e32 v2, 0x7800, v74
	v_mov_b32_e32 v3, v19
	v_lshl_add_u64 v[2:3], s[34:35], 0, v[2:3]
	v_lshl_add_u64 v[2:3], v[2:3], 0, s[8:9]
	v_lshl_add_u64 v[10:11], v[2:3], 0, v[18:19]
	s_mov_b32 s8, 0x120000
	v_add_co_u32_e32 v2, vcc, s8, v10
	s_mov_b64 s[8:9], 0x120000
	s_nop 0
	v_addc_co_u32_e32 v3, vcc, 0, v11, vcc
	global_load_dwordx4 v[76:79], v[2:3], off
	s_nop 0
	global_load_dwordx4 v[80:83], v[20:21], off
	v_lshl_add_u64 v[22:23], v[10:11], 0, s[8:9]
	global_load_dwordx4 v[84:87], v[20:21], off offset:32
	global_load_dwordx4 v[88:91], v[22:23], off offset:32
	global_load_dwordx4 v[92:95], v[22:23], off offset:64
	global_load_dwordx4 v[96:99], v[22:23], off offset:480
	global_load_dwordx4 v[100:103], v[20:21], off offset:64
	global_load_dwordx4 v[104:107], v[20:21], off offset:96
	global_load_dwordx4 v[108:111], v[22:23], off offset:96
	global_load_dwordx4 v[112:115], v[22:23], off offset:128
	global_load_dwordx4 v[120:123], v[20:21], off offset:128
	global_load_dwordx4 v[124:127], v[20:21], off offset:160
	global_load_dwordx4 v[128:131], v[22:23], off offset:160
	global_load_dwordx4 v[132:135], v[22:23], off offset:192
	global_load_dwordx4 v[136:139], v[20:21], off offset:192
	global_load_dwordx4 v[140:143], v[20:21], off offset:224
	global_load_dwordx4 v[144:147], v[22:23], off offset:224
	global_load_dwordx4 v[148:151], v[22:23], off offset:256
	global_load_dwordx4 v[152:155], v[20:21], off offset:256
	global_load_dwordx4 v[156:159], v[20:21], off offset:288
	global_load_dwordx4 v[160:163], v[22:23], off offset:288
	global_load_dwordx4 v[164:167], v[22:23], off offset:320
	global_load_dwordx4 v[168:171], v[20:21], off offset:320
	global_load_dwordx4 v[172:175], v[20:21], off offset:352
	global_load_dwordx4 v[176:179], v[22:23], off offset:352
	global_load_dwordx4 v[184:187], v[22:23], off offset:384
	global_load_dwordx4 v[188:191], v[20:21], off offset:384
	global_load_dwordx4 v[192:195], v[20:21], off offset:416
	global_load_dwordx4 v[204:207], v[22:23], off offset:416
	global_load_dwordx4 v[208:211], v[20:21], off offset:448
	global_load_dwordx4 v[212:215], v[22:23], off offset:448
	global_load_dwordx4 v[216:219], v[20:21], off offset:480
	v_cmp_lt_u32_e32 vcc, 15, v119
	s_nop 0
	s_waitcnt vmcnt(31)
	v_cndmask_b32_e64 v5, v79, 0, vcc
	v_cndmask_b32_e64 v4, v78, 0, vcc
	v_cndmask_b32_e64 v3, v77, 0, vcc
	v_cndmask_b32_e64 v2, v76, 0, vcc
	s_waitcnt vmcnt(28)
	v_cndmask_b32_e64 v33, v91, 0, vcc
	v_cndmask_b32_e64 v32, v90, 0, vcc
	s_waitcnt vmcnt(30)
	v_mfma_f32_32x32x16_bf16 v[2:17], v[80:83], v[2:5], 0
	v_cndmask_b32_e64 v31, v89, 0, vcc
	v_cndmask_b32_e64 v30, v88, 0, vcc
	s_waitcnt vmcnt(27)
	v_cndmask_b32_e64 v37, v95, 0, vcc
	v_cndmask_b32_e64 v36, v94, 0, vcc
	v_cndmask_b32_e64 v35, v93, 0, vcc
	v_cndmask_b32_e64 v34, v92, 0, vcc
	s_waitcnt vmcnt(29)
	v_mfma_f32_32x32x16_bf16 v[2:17], v[84:87], v[30:33], v[2:17]
	s_waitcnt vmcnt(23)
	v_cndmask_b32_e64 v29, v111, 0, vcc
	s_waitcnt vmcnt(25)
	v_mfma_f32_32x32x16_bf16 v[2:17], v[100:103], v[34:37], v[2:17]
	v_cndmask_b32_e64 v28, v110, 0, vcc
	v_cndmask_b32_e64 v27, v109, 0, vcc
	v_cndmask_b32_e64 v26, v108, 0, vcc
	s_waitcnt vmcnt(22)
	v_cndmask_b32_e64 v33, v115, 0, vcc
	v_cndmask_b32_e64 v32, v114, 0, vcc
	v_cndmask_b32_e64 v31, v113, 0, vcc
	s_waitcnt vmcnt(24)
	v_mfma_f32_32x32x16_bf16 v[2:17], v[104:107], v[26:29], v[2:17]
	v_cndmask_b32_e64 v30, v112, 0, vcc
	s_waitcnt vmcnt(19)
	v_cndmask_b32_e64 v29, v131, 0, vcc
	s_waitcnt vmcnt(21)
	v_mfma_f32_32x32x16_bf16 v[2:17], v[120:123], v[30:33], v[2:17]
	v_cndmask_b32_e64 v28, v130, 0, vcc
	v_cndmask_b32_e64 v27, v129, 0, vcc
	v_cndmask_b32_e64 v26, v128, 0, vcc
	s_waitcnt vmcnt(18)
	v_cndmask_b32_e64 v49, v135, 0, vcc
	v_cndmask_b32_e64 v48, v134, 0, vcc
	v_cndmask_b32_e64 v47, v133, 0, vcc
	s_waitcnt vmcnt(20)
	v_mfma_f32_32x32x16_bf16 v[2:17], v[124:127], v[26:29], v[2:17]
	v_cndmask_b32_e64 v46, v132, 0, vcc
	s_waitcnt vmcnt(15)
	v_cndmask_b32_e64 v29, v147, 0, vcc
	s_waitcnt vmcnt(17)
	v_mfma_f32_32x32x16_bf16 v[2:17], v[136:139], v[46:49], v[2:17]
	v_cndmask_b32_e64 v28, v146, 0, vcc
	v_cndmask_b32_e64 v27, v145, 0, vcc
	v_cndmask_b32_e64 v26, v144, 0, vcc
	s_waitcnt vmcnt(14)
	v_cndmask_b32_e64 v45, v151, 0, vcc
	v_cndmask_b32_e64 v44, v150, 0, vcc
	v_cndmask_b32_e64 v43, v149, 0, vcc
	s_waitcnt vmcnt(16)
	v_mfma_f32_32x32x16_bf16 v[2:17], v[140:143], v[26:29], v[2:17]
	v_cndmask_b32_e64 v42, v148, 0, vcc
	s_waitcnt vmcnt(11)
	v_cndmask_b32_e64 v29, v163, 0, vcc
	s_waitcnt vmcnt(13)
	v_mfma_f32_32x32x16_bf16 v[2:17], v[152:155], v[42:45], v[2:17]
	v_cndmask_b32_e64 v28, v162, 0, vcc
	v_cndmask_b32_e64 v27, v161, 0, vcc
	v_cndmask_b32_e64 v26, v160, 0, vcc
	s_waitcnt vmcnt(10)
	v_cndmask_b32_e64 v37, v167, 0, vcc
	v_cndmask_b32_e64 v36, v166, 0, vcc
	v_cndmask_b32_e64 v35, v165, 0, vcc
	s_waitcnt vmcnt(12)
	v_mfma_f32_32x32x16_bf16 v[2:17], v[156:159], v[26:29], v[2:17]
	v_cndmask_b32_e64 v34, v164, 0, vcc
	s_waitcnt vmcnt(7)
	v_cndmask_b32_e64 v29, v179, 0, vcc
	s_waitcnt vmcnt(9)
	v_mfma_f32_32x32x16_bf16 v[2:17], v[168:171], v[34:37], v[2:17]
	v_cndmask_b32_e64 v28, v178, 0, vcc
	v_cndmask_b32_e64 v27, v177, 0, vcc
	v_cndmask_b32_e64 v26, v176, 0, vcc
	s_waitcnt vmcnt(6)
	v_cndmask_b32_e64 v49, v187, 0, vcc
	v_cndmask_b32_e64 v48, v186, 0, vcc
	v_cndmask_b32_e64 v47, v185, 0, vcc
	s_waitcnt vmcnt(8)
	v_mfma_f32_32x32x16_bf16 v[2:17], v[172:175], v[26:29], v[2:17]
	v_cndmask_b32_e64 v46, v184, 0, vcc
	s_waitcnt vmcnt(3)
	v_cndmask_b32_e64 v29, v207, 0, vcc
	s_waitcnt vmcnt(5)
	v_mfma_f32_32x32x16_bf16 v[2:17], v[188:191], v[46:49], v[2:17]
	v_cndmask_b32_e64 v28, v206, 0, vcc
	v_cndmask_b32_e64 v27, v205, 0, vcc
	v_cndmask_b32_e64 v26, v204, 0, vcc
	s_nop 1
	s_waitcnt vmcnt(4)
	v_mfma_f32_32x32x16_bf16 v[2:17], v[192:195], v[26:29], v[2:17]
	s_waitcnt vmcnt(1)
	v_cndmask_b32_e64 v29, v215, 0, vcc
	v_cndmask_b32_e64 v28, v214, 0, vcc
	v_cndmask_b32_e64 v27, v213, 0, vcc
	v_cndmask_b32_e64 v26, v212, 0, vcc
	s_nop 1
	s_waitcnt vmcnt(2)
	v_mfma_f32_32x32x16_bf16 v[2:17], v[208:211], v[26:29], v[2:17]
	s_waitcnt vmcnt(26)
	v_cndmask_b32_e64 v29, v99, 0, vcc
	v_cndmask_b32_e64 v28, v98, 0, vcc
	v_cndmask_b32_e64 v27, v97, 0, vcc
	v_cndmask_b32_e64 v26, v96, 0, vcc
	v_cmp_gt_u32_e32 vcc, 16, v119
	s_waitcnt vmcnt(0)
	v_mfma_f32_32x32x16_bf16 v[2:17], v[216:219], v[26:29], v[2:17]
	s_and_saveexec_b64 s[8:9], vcc
	s_cbranch_execz .LBB0_1007
	s_lshl_b32 s10, s10, 14
	s_add_u32 s6, s6, s10
	s_addc_u32 s7, s7, 0
	v_lshlrev_b32_e32 v18, 2, v119
	v_lshl_or_b32 v20, v24, 2, s6
	v_mov_b32_e32 v21, s7
	v_lshl_add_u64 v[18:19], s[0:1], 0, v[18:19]
	v_lshlrev_b64 v[22:23], 6, v[20:21]
	v_lshl_add_u64 v[22:23], v[18:19], 0, v[22:23]
	s_nop 0
	global_store_dword v[22:23], v2, off
	v_or_b32_e32 v22, 1, v20
	v_mov_b32_e32 v23, s7
	v_lshlrev_b64 v[22:23], 6, v[22:23]
	v_lshl_add_u64 v[22:23], v[18:19], 0, v[22:23]
	global_store_dword v[22:23], v3, off
	v_or_b32_e32 v2, 2, v20
	v_mov_b32_e32 v3, s7
	v_lshlrev_b64 v[2:3], 6, v[2:3]
	v_lshl_add_u64 v[2:3], v[18:19], 0, v[2:3]
	global_store_dword v[2:3], v4, off
	v_or_b32_e32 v2, 3, v20
	v_mov_b32_e32 v3, s7
	v_lshlrev_b64 v[2:3], 6, v[2:3]
	v_lshl_add_u64 v[2:3], v[18:19], 0, v[2:3]
	global_store_dword v[2:3], v5, off
	v_or_b32_e32 v2, 8, v20
	v_mov_b32_e32 v3, s7
	v_lshlrev_b64 v[2:3], 6, v[2:3]
	v_lshl_add_u64 v[2:3], v[18:19], 0, v[2:3]
	global_store_dword v[2:3], v6, off
	v_or_b32_e32 v2, 9, v20
	v_mov_b32_e32 v3, s7
	v_lshlrev_b64 v[2:3], 6, v[2:3]
	v_lshl_add_u64 v[2:3], v[18:19], 0, v[2:3]
	global_store_dword v[2:3], v7, off
	v_or_b32_e32 v2, 10, v20
	v_mov_b32_e32 v3, s7
	v_lshlrev_b64 v[2:3], 6, v[2:3]
	v_lshl_add_u64 v[2:3], v[18:19], 0, v[2:3]
	global_store_dword v[2:3], v8, off
	v_or_b32_e32 v2, 11, v20
	v_mov_b32_e32 v3, s7
	v_lshlrev_b64 v[2:3], 6, v[2:3]
	v_lshl_add_u64 v[2:3], v[18:19], 0, v[2:3]
	global_store_dword v[2:3], v9, off
	v_or_b32_e32 v2, 16, v20
	v_mov_b32_e32 v3, s7
	v_lshlrev_b64 v[2:3], 6, v[2:3]
	v_lshl_add_u64 v[2:3], v[18:19], 0, v[2:3]
	global_store_dword v[2:3], v10, off
	v_or_b32_e32 v2, 17, v20
	v_mov_b32_e32 v3, s7
	v_lshlrev_b64 v[2:3], 6, v[2:3]
	v_lshl_add_u64 v[2:3], v[18:19], 0, v[2:3]
	global_store_dword v[2:3], v11, off
	v_or_b32_e32 v2, 18, v20
	v_mov_b32_e32 v3, s7
	v_lshlrev_b64 v[2:3], 6, v[2:3]
	v_lshl_add_u64 v[2:3], v[18:19], 0, v[2:3]
	global_store_dword v[2:3], v12, off
	v_or_b32_e32 v2, 19, v20
	v_mov_b32_e32 v3, s7
	v_lshlrev_b64 v[2:3], 6, v[2:3]
	v_lshl_add_u64 v[2:3], v[18:19], 0, v[2:3]
	global_store_dword v[2:3], v13, off
	v_or_b32_e32 v2, 24, v20
	v_mov_b32_e32 v3, s7
	v_lshlrev_b64 v[2:3], 6, v[2:3]
	v_lshl_add_u64 v[2:3], v[18:19], 0, v[2:3]
	global_store_dword v[2:3], v14, off
	v_or_b32_e32 v2, 25, v20
	v_mov_b32_e32 v3, s7
	v_lshlrev_b64 v[2:3], 6, v[2:3]
	v_lshl_add_u64 v[2:3], v[18:19], 0, v[2:3]
	global_store_dword v[2:3], v15, off
	v_or_b32_e32 v2, 26, v20
	v_mov_b32_e32 v3, s7
	v_lshlrev_b64 v[2:3], 6, v[2:3]
	v_lshl_add_u64 v[2:3], v[18:19], 0, v[2:3]
	v_or_b32_e32 v20, 27, v20
	global_store_dword v[2:3], v16, off
	v_lshlrev_b64 v[2:3], 6, v[20:21]
	v_lshl_add_u64 v[2:3], v[18:19], 0, v[2:3]
	global_store_dword v[2:3], v17, off
